# fused LayerNorm epilogue: the four row-statistics granules read with one wait
# baseline (speedup 1.0000x reference)
;     __device__ __forceinline__ void fused(AccT& acc, const Unit& u, int wr, int wc, int fr, int fq, LAS unsigned char* lx, int tid) const {
;     ...
;         if (tid < 256) {
;             const unsigned long long* slot = xbuf + (size_t)(u.pm * 256 + tid) * 4; float S1 = 0.f, S2 = 0.f;
; #pragma unroll
;             for (int t = 0; t < 4; ++t) { const unsigned long long w = __hip_atomic_load(slot + t, __ATOMIC_RELAXED, __HIP_MEMORY_SCOPE_AGENT); S1 += __uint_as_float((unsigned)w); S2 += __uint_as_float((unsigned)(w >> 32)); }
;             const float mean = S1 * (1.0f / DM), var = fmaxf(S2 * (1.0f / DM) - mean * mean, 0.f);
;             Sx[tid] = (f32x2){mean, 1.0f / sqrtf(var + LN_EPS)};
;         }
.LBB0_116:
	s_or_b64 exec, exec, s[10:11]
	s_waitcnt vmcnt(0) lgkmcnt(0)
	s_barrier
	s_and_saveexec_b64 s[10:11], s[0:1]
	s_cbranch_execz .LBB0_118
	v_readlane_b32 s0, v255, 17
	v_lshlrev_b64 v[2:3], 5, v[2:3]
	v_readlane_b32 s1, v255, 18
	s_nop 1
	v_lshl_add_u64 v[2:3], s[0:1], 0, v[2:3]
	s_waitcnt lgkmcnt(0)
	flat_load_dwordx2 v[4:5], v[2:3] sc1
	flat_load_dwordx2 v[8:9], v[2:3] offset:8 sc1
	flat_load_dwordx2 v[10:11], v[2:3] offset:16 sc1
	flat_load_dwordx2 v[12:13], v[2:3] offset:24 sc1
	s_mov_b32 s0, 0x3a800000
	s_waitcnt vmcnt(0) lgkmcnt(0)
	v_add_f32_e32 v6, 0, v4
	v_add_f32_e32 v7, 0, v5
	v_add_f32_e32 v6, v6, v8
	v_add_f32_e32 v7, v7, v9
	v_add_f32_e32 v4, v6, v10
	v_add_f32_e32 v5, v7, v11
	v_add_f32_e32 v2, v4, v12
	v_mul_f32_e32 v2, 0x3a800000, v2
	v_add_f32_e32 v3, v5, v13
	v_mul_f32_e32 v4, v2, v2
	v_fma_f32 v3, v3, s0, -v4
	v_max_f32_e32 v3, 0, v3
	v_add_f32_e32 v3, 0x3727c5ac, v3
	s_mov_b32 s0, 0xf800000
	v_cmp_gt_f32_e32 vcc, s0, v3
	v_mul_f32_e32 v4, 0x4f800000, v3
	s_nop 0
	v_cndmask_b32_e32 v3, v3, v4, vcc
	v_sqrt_f32_e32 v4, v3
	s_nop 0
	v_add_u32_e32 v5, -1, v4
	v_fma_f32 v6, -v5, v4, v3
	v_cmp_ge_f32_e64 s[0:1], 0, v6
	v_add_u32_e32 v6, 1, v4
	s_nop 0
	v_cndmask_b32_e64 v5, v4, v5, s[0:1]
	v_fma_f32 v4, -v6, v4, v3
	v_cmp_lt_f32_e64 s[0:1], 0, v4
	s_nop 1
	v_cndmask_b32_e64 v4, v5, v6, s[0:1]
	v_mul_f32_e32 v5, 0x37800000, v4
	v_cndmask_b32_e32 v4, v4, v5, vcc
	v_cmp_class_f32_e32 vcc, v3, v232
	s_nop 1
	v_cndmask_b32_e32 v3, v4, v3, vcc
	v_div_scale_f32 v4, s[0:1], v3, v3, 1.0
	v_rcp_f32_e32 v5, v4
	s_nop 0
	v_fma_f32 v6, -v4, v5, 1.0
	v_fmac_f32_e32 v5, v6, v5
	v_div_scale_f32 v6, vcc, 1.0, v3, 1.0
	v_mul_f32_e32 v7, v6, v5
	v_fma_f32 v8, -v4, v7, v6
	v_fmac_f32_e32 v7, v8, v5
	v_fma_f32 v4, -v4, v7, v6
	v_div_fmas_f32 v4, v4, v5, v7
	v_div_fixup_f32 v3, v4, v3, 1.0
	v_lshl_add_u32 v4, v239, 3, 0
	v_add_u32_e32 v4, 0x22000, v4
	ds_write_b64 v4, v[2:3]
